# grid barrier entry: workspace-pointer kernarg load hoisted above the store wait and workgroup barrier (9 of 11 instances)
# speedup vs baseline: 1.0019x; 1.0019x over previous
; __device__ __forceinline__ void xcd_barrier(const XcdBarrier& b) {
;     asm volatile("s_waitcnt vmcnt(0)" ::: "memory");
;     __syncthreads();
;     if (threadIdx.x == 0) {
;         unsigned* bar = b.bar;
;         __builtin_amdgcn_s_waitcnt(0);
;         unsigned nloc = b.st[0], nx = b.st[1];
;         if (nloc == 0u) { xcd_barrier_complete(bar, b.x, nloc, nx); b.st[0] = nloc; b.st[1] = nx; }
.LBB0_101:
	s_cmp_lg_u32 s21, 1
	s_cbranch_scc0 .LBB0_155
	s_mov_b32 s6, 0
	s_ashr_i32 s7, s6, 31
	s_lshl_b64 s[6:7], s[6:7], 3
	s_add_u32 s6, s0, s6
	s_addc_u32 s7, s1, s7
	s_load_dwordx2 s[6:7], s[6:7], 0xc8
	s_getreg_b32 s3, hwreg(HW_REG_XCC_ID, 0, 4)
	s_waitcnt vmcnt(0)
	s_barrier
	s_and_saveexec_b64 s[4:5], s[86:87]
	s_cbranch_execz .LBB0_154
	s_add_i32 s8, 0, 0x23ff0
	v_mov_b32_e32 v0, s8
	s_waitcnt vmcnt(0) expcnt(0) lgkmcnt(0)
	ds_read_b32 v2, v0
	s_add_i32 s8, 0, 0x23ff4
	v_mov_b32_e32 v0, s8
	ds_read_b32 v0, v0
	s_and_b32 s3, s3, 15
	s_waitcnt lgkmcnt(1)
	v_cmp_ne_u32_e32 vcc, 0, v2
	s_cbranch_vccnz .LBB0_118
	s_add_u32 s8, s6, 0x2e800200
	s_addc_u32 s9, s7, 0
	s_add_u32 s10, s6, 0x2e800400
	s_addc_u32 s11, s7, 0
	s_add_u32 s12, s6, 0x2e800500
	s_addc_u32 s13, s7, 0
	s_add_u32 s14, s6, 0x2e800600
	s_addc_u32 s15, s7, 0
	s_add_u32 s16, s6, 0x2e800700
	s_addc_u32 s17, s7, 0
	s_add_u32 s18, s6, 0x2e800800
	s_addc_u32 s19, s7, 0
	s_add_u32 s24, s6, 0x2e800900
	s_addc_u32 s25, s7, 0
	s_add_u32 s26, s6, 0x2e800a00
	s_addc_u32 s27, s7, 0
	s_add_u32 s28, s6, 0x2e800b00
	s_addc_u32 s29, s7, 0
	s_add_u32 s30, s6, 0x2e800c00
	s_addc_u32 s31, s7, 0
	s_add_u32 s34, s6, 0x2e800d00
	s_addc_u32 s35, s7, 0
	s_add_u32 s36, s6, 0x2e800e00
	s_addc_u32 s37, s7, 0
	s_add_u32 s38, s6, 0x2e800f00
	s_addc_u32 s39, s7, 0
	s_add_u32 s40, s6, 0x2e801000
	s_addc_u32 s41, s7, 0
	s_add_u32 s42, s6, 0x2e801100
	s_addc_u32 s43, s7, 0
	s_add_u32 s44, s6, 0x2e801200
	s_addc_u32 s45, s7, 0
	s_mul_i32 s33, s23, s2
	s_add_u32 s46, s6, 0x2e801300
	s_mul_i32 s33, s33, s22
	s_addc_u32 s47, s7, 0
	s_mov_b32 s54, 1
	v_mov_b32_e32 v16, 0
	s_branch .LBB0_106

; __device__ __forceinline__ void xcd_barrier(const XcdBarrier& b) {
;     asm volatile("s_waitcnt vmcnt(0)" ::: "memory");
;     __syncthreads();
;     if (threadIdx.x == 0) {
;         unsigned* bar = b.bar;
;         __builtin_amdgcn_s_waitcnt(0);
;         unsigned nloc = b.st[0], nx = b.st[1];
;         if (nloc == 0u) { xcd_barrier_complete(bar, b.x, nloc, nx); b.st[0] = nloc; b.st[1] = nx; }
.LBB0_186:
	s_add_i32 s2, s82, 1
	s_cmp_ge_i32 s2, s21
	s_cbranch_scc1 .LBB0_241
	s_mov_b32 s6, s19
	s_ashr_i32 s7, s6, 31
	s_lshl_b64 s[6:7], s[6:7], 3
	s_add_u32 s6, s0, s6
	s_addc_u32 s7, s1, s7
	s_load_dwordx2 s[6:7], s[6:7], 0xc8
	s_getreg_b32 s3, hwreg(HW_REG_XCC_ID, 0, 4)
	s_waitcnt vmcnt(0)
	s_barrier
	s_and_saveexec_b64 s[4:5], s[86:87]
	s_cbranch_execz .LBB0_240
	v_readlane_b32 s8, v255, 11
	v_mov_b32_e32 v0, s8
	s_waitcnt vmcnt(0) expcnt(0) lgkmcnt(0)
	ds_read_b32 v2, v0
	v_readlane_b32 s8, v255, 12
	s_and_b32 s3, s3, 15
	s_waitcnt lgkmcnt(0)
	v_cmp_ne_u32_e32 vcc, 0, v2
	v_mov_b32_e32 v0, s8
	ds_read_b32 v0, v0
	s_cbranch_vccnz .LBB0_204
	s_add_u32 s8, s6, 0x2e800200
	s_addc_u32 s9, s7, 0
	s_add_u32 s10, s6, 0x2e800400
	s_addc_u32 s11, s7, 0
	s_add_u32 s12, s6, 0x2e800500
	s_addc_u32 s13, s7, 0
	s_add_u32 s14, s6, 0x2e800600
	s_addc_u32 s15, s7, 0
	s_add_u32 s16, s6, 0x2e800700
	s_addc_u32 s17, s7, 0
	s_add_u32 s34, s6, 0x2e800800
	s_addc_u32 s35, s7, 0
	s_add_u32 s52, s6, 0x2e800900
	s_addc_u32 s53, s7, 0
	s_add_u32 s54, s6, 0x2e800a00
	s_addc_u32 s55, s7, 0
	s_add_u32 s56, s6, 0x2e800b00
	s_addc_u32 s57, s7, 0
	s_add_u32 s60, s6, 0x2e800c00
	s_addc_u32 s61, s7, 0
	s_add_u32 s62, s6, 0x2e800d00
	s_addc_u32 s63, s7, 0
	s_add_u32 s64, s6, 0x2e800e00
	s_addc_u32 s65, s7, 0
	s_add_u32 s66, s6, 0x2e800f00
	s_addc_u32 s67, s7, 0
	s_add_u32 s68, s6, 0x2e801000
	s_addc_u32 s69, s7, 0
	s_add_u32 s70, s6, 0x2e801100
	s_addc_u32 s71, s7, 0
	s_add_u32 s72, s6, 0x2e801200
	s_addc_u32 s73, s7, 0
	s_add_u32 s74, s6, 0x2e801300
	s_addc_u32 s75, s7, 0
	s_mov_b32 s18, 1
	s_branch .LBB0_192

; __device__ __forceinline__ void xcd_barrier(const XcdBarrier& b) {
;     asm volatile("s_waitcnt vmcnt(0)" ::: "memory");
;     __syncthreads();
;     if (threadIdx.x == 0) {
;         unsigned* bar = b.bar;
;         __builtin_amdgcn_s_waitcnt(0);
;         unsigned nloc = b.st[0], nx = b.st[1];
;         if (nloc == 0u) { xcd_barrier_complete(bar, b.x, nloc, nx); b.st[0] = nloc; b.st[1] = nx; }
.LBB0_286:
	s_add_i32 s67, s82, 2
	s_cmp_ge_i32 s67, s21
	s_cbranch_scc1 .LBB0_341
	s_waitcnt lgkmcnt(0)
	s_mov_b32 s6, s19
	s_ashr_i32 s7, s6, 31
	s_lshl_b64 s[6:7], s[6:7], 3
	s_add_u32 s6, s0, s6
	s_addc_u32 s7, s1, s7
	s_load_dwordx2 s[6:7], s[6:7], 0xc8
	s_getreg_b32 s2, hwreg(HW_REG_XCC_ID, 0, 4)
	s_waitcnt vmcnt(0)
	s_barrier
	s_and_saveexec_b64 s[4:5], s[86:87]
	s_cbranch_execz .LBB0_340
	v_readlane_b32 s3, v255, 11
	v_mov_b32_e32 v0, s3
	s_waitcnt vmcnt(0) expcnt(0) lgkmcnt(0)
	ds_read_b32 v2, v0
	v_readlane_b32 s3, v255, 12
	s_and_b32 s2, s2, 15
	s_waitcnt lgkmcnt(0)
	v_cmp_ne_u32_e32 vcc, 0, v2
	v_mov_b32_e32 v0, s3
	ds_read_b32 v0, v0
	s_cbranch_vccnz .LBB0_304
	s_add_u32 s8, s6, 0x2e800200
	s_addc_u32 s9, s7, 0
	s_add_u32 s10, s6, 0x2e800400
	s_addc_u32 s11, s7, 0
	s_add_u32 s12, s6, 0x2e800500
	s_addc_u32 s13, s7, 0
	s_add_u32 s14, s6, 0x2e800600
	s_addc_u32 s15, s7, 0
	s_add_u32 s16, s6, 0x2e800700
	s_addc_u32 s17, s7, 0
	s_add_u32 s34, s6, 0x2e800800
	s_addc_u32 s35, s7, 0
	s_add_u32 s52, s6, 0x2e800900
	s_addc_u32 s53, s7, 0
	s_add_u32 s54, s6, 0x2e800a00
	s_addc_u32 s55, s7, 0
	s_add_u32 s56, s6, 0x2e800b00
	s_addc_u32 s57, s7, 0
	s_add_u32 s60, s6, 0x2e800c00
	s_addc_u32 s61, s7, 0
	s_add_u32 s62, s6, 0x2e800d00
	s_addc_u32 s63, s7, 0
	s_add_u32 s64, s6, 0x2e800e00
	s_addc_u32 s65, s7, 0
	s_add_u32 s66, s6, 0x2e800f00
	s_mov_b32 s23, s67
	s_addc_u32 s67, s7, 0
	s_add_u32 s68, s6, 0x2e801000
	s_addc_u32 s69, s7, 0
	s_add_u32 s70, s6, 0x2e801100
	s_addc_u32 s71, s7, 0
	s_add_u32 s72, s6, 0x2e801200
	s_addc_u32 s73, s7, 0
	s_add_u32 s74, s6, 0x2e801300
	s_addc_u32 s75, s7, 0
	s_mov_b32 s3, 1
	s_branch .LBB0_292

; __device__ __forceinline__ void xcd_barrier(const XcdBarrier& b) {
;     asm volatile("s_waitcnt vmcnt(0)" ::: "memory");
;     __syncthreads();
;     if (threadIdx.x == 0) {
;         unsigned* bar = b.bar;
;         __builtin_amdgcn_s_waitcnt(0);
;         unsigned nloc = b.st[0], nx = b.st[1];
;         if (nloc == 0u) { xcd_barrier_complete(bar, b.x, nloc, nx); b.st[0] = nloc; b.st[1] = nx; }
.LBB0_402:
	s_add_i32 s2, s82, 1
	s_cmp_ge_i32 s2, s21
	s_cbranch_scc1 .LBB0_457
	s_mov_b32 s6, s19
	s_ashr_i32 s7, s6, 31
	s_lshl_b64 s[6:7], s[6:7], 3
	s_add_u32 s6, s0, s6
	s_addc_u32 s7, s1, s7
	s_load_dwordx2 s[6:7], s[6:7], 0xc8
	s_getreg_b32 s3, hwreg(HW_REG_XCC_ID, 0, 4)
	s_waitcnt vmcnt(0)
	s_waitcnt vmcnt(0)
	s_barrier
	s_and_saveexec_b64 s[4:5], s[86:87]
	s_cbranch_execz .LBB0_456
	v_readlane_b32 s8, v255, 11
	v_mov_b32_e32 v0, s8
	s_waitcnt vmcnt(0) expcnt(0) lgkmcnt(0)
	ds_read_b32 v2, v0
	v_readlane_b32 s8, v255, 12
	s_and_b32 s3, s3, 15
	s_waitcnt lgkmcnt(0)
	v_cmp_ne_u32_e32 vcc, 0, v2
	v_mov_b32_e32 v0, s8
	ds_read_b32 v0, v0
	s_cbranch_vccnz .LBB0_420
	s_add_u32 s8, s6, 0x2e800200
	s_addc_u32 s9, s7, 0
	s_add_u32 s10, s6, 0x2e800400
	s_addc_u32 s11, s7, 0
	s_add_u32 s12, s6, 0x2e800500
	s_addc_u32 s13, s7, 0
	s_add_u32 s14, s6, 0x2e800600
	s_addc_u32 s15, s7, 0
	s_add_u32 s16, s6, 0x2e800700
	s_addc_u32 s17, s7, 0
	s_add_u32 s34, s6, 0x2e800800
	s_addc_u32 s35, s7, 0
	s_add_u32 s52, s6, 0x2e800900
	s_addc_u32 s53, s7, 0
	s_add_u32 s54, s6, 0x2e800a00
	s_addc_u32 s55, s7, 0
	s_add_u32 s56, s6, 0x2e800b00
	s_addc_u32 s57, s7, 0
	s_add_u32 s60, s6, 0x2e800c00
	s_addc_u32 s61, s7, 0
	s_add_u32 s62, s6, 0x2e800d00
	s_addc_u32 s63, s7, 0
	s_add_u32 s64, s6, 0x2e800e00
	s_addc_u32 s65, s7, 0
	s_add_u32 s66, s6, 0x2e800f00
	s_addc_u32 s67, s7, 0
	s_add_u32 s68, s6, 0x2e801000
	s_addc_u32 s69, s7, 0
	s_add_u32 s70, s6, 0x2e801100
	s_addc_u32 s71, s7, 0
	s_add_u32 s72, s6, 0x2e801200
	s_addc_u32 s73, s7, 0
	s_add_u32 s74, s6, 0x2e801300
	s_addc_u32 s75, s7, 0
	s_mov_b32 s18, 1
	s_branch .LBB0_408

; __device__ __forceinline__ void xcd_barrier(const XcdBarrier& b) {
;     asm volatile("s_waitcnt vmcnt(0)" ::: "memory");
;     __syncthreads();
;     if (threadIdx.x == 0) {
;         unsigned* bar = b.bar;
;         __builtin_amdgcn_s_waitcnt(0);
;         unsigned nloc = b.st[0], nx = b.st[1];
;         if (nloc == 0u) { xcd_barrier_complete(bar, b.x, nloc, nx); b.st[0] = nloc; b.st[1] = nx; }
.LBB0_489:
	s_add_i32 s2, s82, 2
	s_cmp_ge_i32 s2, s21
	s_cbranch_scc1 .LBB0_544
	s_mov_b32 s6, s19
	s_ashr_i32 s7, s6, 31
	s_lshl_b64 s[6:7], s[6:7], 3
	s_add_u32 s6, s0, s6
	s_addc_u32 s7, s1, s7
	s_load_dwordx2 s[6:7], s[6:7], 0xc8
	s_getreg_b32 s3, hwreg(HW_REG_XCC_ID, 0, 4)
	s_waitcnt vmcnt(0)
	s_waitcnt vmcnt(0)
	s_barrier
	s_and_saveexec_b64 s[4:5], s[86:87]
	s_cbranch_execz .LBB0_543
	v_readlane_b32 s8, v255, 11
	v_mov_b32_e32 v0, s8
	s_waitcnt vmcnt(0) expcnt(0) lgkmcnt(0)
	ds_read_b32 v2, v0
	v_readlane_b32 s8, v255, 12
	s_and_b32 s3, s3, 15
	s_waitcnt lgkmcnt(0)
	v_cmp_ne_u32_e32 vcc, 0, v2
	v_mov_b32_e32 v0, s8
	ds_read_b32 v0, v0
	s_cbranch_vccnz .LBB0_507
	s_add_u32 s8, s6, 0x2e800200
	s_addc_u32 s9, s7, 0
	s_add_u32 s10, s6, 0x2e800400
	s_addc_u32 s11, s7, 0
	s_add_u32 s12, s6, 0x2e800500
	s_addc_u32 s13, s7, 0
	s_add_u32 s14, s6, 0x2e800600
	s_addc_u32 s15, s7, 0
	s_add_u32 s16, s6, 0x2e800700
	s_addc_u32 s17, s7, 0
	s_add_u32 s34, s6, 0x2e800800
	s_addc_u32 s35, s7, 0
	s_add_u32 s52, s6, 0x2e800900
	s_addc_u32 s53, s7, 0
	s_add_u32 s54, s6, 0x2e800a00
	s_addc_u32 s55, s7, 0
	s_add_u32 s56, s6, 0x2e800b00
	s_addc_u32 s57, s7, 0
	s_add_u32 s60, s6, 0x2e800c00
	s_addc_u32 s61, s7, 0
	s_add_u32 s62, s6, 0x2e800d00
	s_addc_u32 s63, s7, 0
	s_add_u32 s64, s6, 0x2e800e00
	s_addc_u32 s65, s7, 0
	s_add_u32 s66, s6, 0x2e800f00
	s_addc_u32 s67, s7, 0
	s_add_u32 s68, s6, 0x2e801000
	s_addc_u32 s69, s7, 0
	s_add_u32 s70, s6, 0x2e801100
	s_addc_u32 s71, s7, 0
	s_add_u32 s72, s6, 0x2e801200
	s_addc_u32 s73, s7, 0
	s_add_u32 s74, s6, 0x2e801300
	s_addc_u32 s75, s7, 0
	s_mov_b32 s18, 1
	s_branch .LBB0_495

; __device__ __forceinline__ void xcd_barrier(const XcdBarrier& b) {
;     asm volatile("s_waitcnt vmcnt(0)" ::: "memory");
;     __syncthreads();
;     if (threadIdx.x == 0) {
;         unsigned* bar = b.bar;
;         __builtin_amdgcn_s_waitcnt(0);
;         unsigned nloc = b.st[0], nx = b.st[1];
;         if (nloc == 0u) { xcd_barrier_complete(bar, b.x, nloc, nx); b.st[0] = nloc; b.st[1] = nx; }
.LBB0_605:
	s_add_i32 s67, s82, 3
	s_cmp_ge_i32 s67, s21
	s_cbranch_scc1 .LBB0_609
	s_waitcnt lgkmcnt(0)
	s_mov_b32 s6, s19
	s_ashr_i32 s7, s6, 31
	s_lshl_b64 s[6:7], s[6:7], 3
	s_add_u32 s6, s0, s6
	s_addc_u32 s7, s1, s7
	s_load_dwordx2 s[6:7], s[6:7], 0xc8
	s_getreg_b32 s2, hwreg(HW_REG_XCC_ID, 0, 4)
	s_waitcnt vmcnt(0)
	s_waitcnt vmcnt(0)
	s_barrier
	s_and_saveexec_b64 s[4:5], s[86:87]
	s_cbranch_execz .LBB0_1498
	v_readlane_b32 s3, v255, 11
	v_mov_b32_e32 v0, s3
	s_waitcnt vmcnt(0) expcnt(0) lgkmcnt(0)
	ds_read_b32 v2, v0
	v_readlane_b32 s3, v255, 12
	s_and_b32 s2, s2, 15
	s_waitcnt lgkmcnt(0)
	v_cmp_ne_u32_e32 vcc, 0, v2
	v_mov_b32_e32 v0, s3
	ds_read_b32 v0, v0
	s_cbranch_vccnz .LBB0_687
	s_add_u32 s8, s6, 0x2e800200
	s_addc_u32 s9, s7, 0
	s_add_u32 s10, s6, 0x2e800400
	s_addc_u32 s11, s7, 0
	s_add_u32 s12, s6, 0x2e800500
	s_addc_u32 s13, s7, 0
	s_add_u32 s14, s6, 0x2e800600
	s_addc_u32 s15, s7, 0
	s_add_u32 s16, s6, 0x2e800700
	s_addc_u32 s17, s7, 0
	s_add_u32 s34, s6, 0x2e800800
	s_addc_u32 s35, s7, 0
	s_add_u32 s52, s6, 0x2e800900
	s_addc_u32 s53, s7, 0
	s_add_u32 s54, s6, 0x2e800a00
	s_addc_u32 s55, s7, 0
	s_add_u32 s56, s6, 0x2e800b00
	s_addc_u32 s57, s7, 0
	s_add_u32 s60, s6, 0x2e800c00
	s_addc_u32 s61, s7, 0
	s_add_u32 s62, s6, 0x2e800d00
	s_addc_u32 s63, s7, 0
	s_add_u32 s64, s6, 0x2e800e00
	s_addc_u32 s65, s7, 0
	s_add_u32 s66, s6, 0x2e800f00
	s_mov_b32 s23, s67
	s_addc_u32 s67, s7, 0
	s_add_u32 s68, s6, 0x2e801000
	s_addc_u32 s69, s7, 0
	s_add_u32 s70, s6, 0x2e801100
	s_addc_u32 s71, s7, 0
	s_add_u32 s72, s6, 0x2e801200
	s_addc_u32 s73, s7, 0
	s_add_u32 s74, s6, 0x2e801300
	s_addc_u32 s75, s7, 0
	s_mov_b32 s3, 1
	s_branch .LBB0_645

; __device__ __forceinline__ void xcd_barrier(const XcdBarrier& b) {
;     asm volatile("s_waitcnt vmcnt(0)" ::: "memory");
;     __syncthreads();
;     if (threadIdx.x == 0) {
;         unsigned* bar = b.bar;
;         __builtin_amdgcn_s_waitcnt(0);
;         unsigned nloc = b.st[0], nx = b.st[1];
;         if (nloc == 0u) { xcd_barrier_complete(bar, b.x, nloc, nx); b.st[0] = nloc; b.st[1] = nx; }
.LBB0_652:
	s_add_i32 s2, s82, 1
	s_cmp_ge_i32 s2, s21
	s_cbranch_scc1 .LBB0_741
	s_mov_b32 s6, s19
	s_ashr_i32 s7, s6, 31
	s_lshl_b64 s[6:7], s[6:7], 3
	s_add_u32 s6, s0, s6
	s_addc_u32 s7, s1, s7
	s_load_dwordx2 s[6:7], s[6:7], 0xc8
	s_getreg_b32 s3, hwreg(HW_REG_XCC_ID, 0, 4)
	s_waitcnt vmcnt(0)
	s_waitcnt vmcnt(0)
	s_barrier
	s_and_saveexec_b64 s[4:5], s[86:87]
	s_cbranch_execz .LBB0_740
	v_readlane_b32 s8, v255, 11
	v_mov_b32_e32 v0, s8
	s_waitcnt vmcnt(0) expcnt(0) lgkmcnt(0)
	ds_read_b32 v2, v0
	v_readlane_b32 s8, v255, 12
	s_and_b32 s3, s3, 15
	s_waitcnt lgkmcnt(0)
	v_cmp_ne_u32_e32 vcc, 0, v2
	v_mov_b32_e32 v0, s8
	ds_read_b32 v0, v0
	s_cbranch_vccnz .LBB0_670
	s_add_u32 s8, s6, 0x2e800200
	s_addc_u32 s9, s7, 0
	s_add_u32 s10, s6, 0x2e800400
	s_addc_u32 s11, s7, 0
	s_add_u32 s14, s6, 0x2e800500
	s_addc_u32 s15, s7, 0
	s_add_u32 s16, s6, 0x2e800600
	s_addc_u32 s17, s7, 0
	s_add_u32 s34, s6, 0x2e800700
	s_addc_u32 s35, s7, 0
	s_add_u32 s52, s6, 0x2e800800
	s_addc_u32 s53, s7, 0
	s_add_u32 s54, s6, 0x2e800900
	s_addc_u32 s55, s7, 0
	s_add_u32 s56, s6, 0x2e800a00
	s_addc_u32 s57, s7, 0
	s_add_u32 s60, s6, 0x2e800b00
	s_addc_u32 s61, s7, 0
	s_add_u32 s62, s6, 0x2e800c00
	s_addc_u32 s63, s7, 0
	s_add_u32 s64, s6, 0x2e800d00
	s_addc_u32 s65, s7, 0
	s_add_u32 s66, s6, 0x2e800e00
	s_addc_u32 s67, s7, 0
	s_add_u32 s68, s6, 0x2e800f00
	s_addc_u32 s69, s7, 0
	s_add_u32 s70, s6, 0x2e801000
	s_addc_u32 s71, s7, 0
	s_add_u32 s72, s6, 0x2e801100
	s_addc_u32 s73, s7, 0
	s_add_u32 s74, s6, 0x2e801200
	s_addc_u32 s75, s7, 0
	s_add_u32 s76, s6, 0x2e801300
	s_addc_u32 s77, s7, 0
	s_mov_b32 s18, 1
	s_branch .LBB0_658

; __device__ __forceinline__ void xcd_barrier(const XcdBarrier& b) {
;     asm volatile("s_waitcnt vmcnt(0)" ::: "memory");
;     __syncthreads();
;     if (threadIdx.x == 0) {
;         unsigned* bar = b.bar;
;         __builtin_amdgcn_s_waitcnt(0);
;         unsigned nloc = b.st[0], nx = b.st[1];
;         if (nloc == 0u) { xcd_barrier_complete(bar, b.x, nloc, nx); b.st[0] = nloc; b.st[1] = nx; }
.LBB0_1221:
	s_add_i32 s2, s67, 1
	s_cmp_ge_i32 s2, s21
	s_cbranch_scc1 .LBB0_1275
	s_mov_b32 s6, s19
	s_ashr_i32 s7, s6, 31
	s_lshl_b64 s[6:7], s[6:7], 3
	s_add_u32 s6, s0, s6
	s_addc_u32 s7, s1, s7
	s_load_dwordx2 s[6:7], s[6:7], 0xc8
	s_getreg_b32 s3, hwreg(HW_REG_XCC_ID, 0, 4)
	s_waitcnt vmcnt(0)
	s_barrier
	s_and_saveexec_b64 s[4:5], s[86:87]
	s_cbranch_execz .LBB0_1274
	v_readlane_b32 s8, v255, 11
	v_mov_b32_e32 v0, s8
	s_waitcnt vmcnt(0) expcnt(0) lgkmcnt(0)
	ds_read_b32 v2, v0
	v_readlane_b32 s8, v255, 12
	s_and_b32 s3, s3, 15
	s_waitcnt lgkmcnt(0)
	v_cmp_ne_u32_e32 vcc, 0, v2
	v_mov_b32_e32 v0, s8
	ds_read_b32 v0, v0
	s_cbranch_vccnz .LBB0_1238
	s_add_u32 s8, s6, 0x2e800200
	s_addc_u32 s9, s7, 0
	s_add_u32 s10, s6, 0x2e800400
	s_addc_u32 s11, s7, 0
	s_add_u32 s12, s6, 0x2e800500
	s_addc_u32 s13, s7, 0
	s_add_u32 s14, s6, 0x2e800600
	s_addc_u32 s15, s7, 0
	s_add_u32 s16, s6, 0x2e800700
	s_addc_u32 s17, s7, 0
	s_add_u32 s34, s6, 0x2e800800
	s_addc_u32 s35, s7, 0
	s_add_u32 s52, s6, 0x2e800900
	s_addc_u32 s53, s7, 0
	s_add_u32 s54, s6, 0x2e800a00
	s_addc_u32 s55, s7, 0
	s_add_u32 s56, s6, 0x2e800b00
	s_addc_u32 s57, s7, 0
	s_add_u32 s58, s6, 0x2e800c00
	s_addc_u32 s59, s7, 0
	s_add_u32 s60, s6, 0x2e800d00
	s_addc_u32 s61, s7, 0
	s_add_u32 s62, s6, 0x2e800e00
	s_addc_u32 s63, s7, 0
	s_add_u32 s64, s6, 0x2e800f00
	s_addc_u32 s65, s7, 0
	s_add_u32 s66, s6, 0x2e801000
	s_mov_b32 s24, s67
	s_addc_u32 s67, s7, 0
	s_add_u32 s68, s6, 0x2e801100
	s_addc_u32 s69, s7, 0
	s_add_u32 s70, s6, 0x2e801200
	s_addc_u32 s71, s7, 0
	s_add_u32 s72, s6, 0x2e801300
	s_addc_u32 s73, s7, 0
	s_mov_b32 s18, 1
	s_branch .LBB0_1226

; __device__ __forceinline__ void xcd_barrier(const XcdBarrier& b) {
;     asm volatile("s_waitcnt vmcnt(0)" ::: "memory");
;     __syncthreads();
;     if (threadIdx.x == 0) {
;         unsigned* bar = b.bar;
;         __builtin_amdgcn_s_waitcnt(0);
;         unsigned nloc = b.st[0], nx = b.st[1];
;         if (nloc == 0u) { xcd_barrier_complete(bar, b.x, nloc, nx); b.st[0] = nloc; b.st[1] = nx; }
.LBB0_1289:
	s_or_b64 exec, exec, s[6:7]
	s_add_i32 s2, s67, 2
	s_cmp_ge_i32 s2, s21
	s_cbranch_scc1 .LBB0_1343
	s_mov_b32 s6, s19
	s_ashr_i32 s7, s6, 31
	s_lshl_b64 s[6:7], s[6:7], 3
	s_add_u32 s6, s0, s6
	s_addc_u32 s7, s1, s7
	s_load_dwordx2 s[6:7], s[6:7], 0xc8
	s_getreg_b32 s3, hwreg(HW_REG_XCC_ID, 0, 4)
	s_waitcnt vmcnt(0)
	s_waitcnt vmcnt(0)
	s_barrier
	s_and_saveexec_b64 s[4:5], s[86:87]
	s_cbranch_execz .LBB0_1342
	v_readlane_b32 s8, v255, 11
	v_mov_b32_e32 v0, s8
	s_waitcnt vmcnt(0) expcnt(0) lgkmcnt(0)
	ds_read_b32 v2, v0
	v_readlane_b32 s8, v255, 12
	s_and_b32 s3, s3, 15
	s_waitcnt lgkmcnt(0)
	v_cmp_ne_u32_e32 vcc, 0, v2
	v_mov_b32_e32 v0, s8
	ds_read_b32 v0, v0
	s_cbranch_vccnz .LBB0_1306
	s_add_u32 s8, s6, 0x2e800200
	s_addc_u32 s9, s7, 0
	s_add_u32 s10, s6, 0x2e800400
	s_addc_u32 s11, s7, 0
	s_add_u32 s12, s6, 0x2e800500
	s_addc_u32 s13, s7, 0
	s_add_u32 s14, s6, 0x2e800600
	s_addc_u32 s15, s7, 0
	s_add_u32 s16, s6, 0x2e800700
	s_addc_u32 s17, s7, 0
	s_add_u32 s34, s6, 0x2e800800
	s_addc_u32 s35, s7, 0
	s_add_u32 s52, s6, 0x2e800900
	s_addc_u32 s53, s7, 0
	s_add_u32 s54, s6, 0x2e800a00
	s_addc_u32 s55, s7, 0
	s_add_u32 s56, s6, 0x2e800b00
	s_addc_u32 s57, s7, 0
	s_add_u32 s58, s6, 0x2e800c00
	s_addc_u32 s59, s7, 0
	s_add_u32 s60, s6, 0x2e800d00
	s_addc_u32 s61, s7, 0
	s_add_u32 s62, s6, 0x2e800e00
	s_addc_u32 s63, s7, 0
	s_add_u32 s64, s6, 0x2e800f00
	s_addc_u32 s65, s7, 0
	s_add_u32 s66, s6, 0x2e801000
	s_mov_b32 s24, s67
	s_addc_u32 s67, s7, 0
	s_add_u32 s68, s6, 0x2e801100
	s_addc_u32 s69, s7, 0
	s_add_u32 s70, s6, 0x2e801200
	s_addc_u32 s71, s7, 0
	s_add_u32 s72, s6, 0x2e801300
	s_addc_u32 s73, s7, 0
	s_mov_b32 s18, 1
	s_branch .LBB0_1294
